# in-projection GEMM: no per-segment priority flips, one static s_setprio 1 for waves 4-7
# speedup vs baseline: 1.0007x; 1.0007x over previous
; __device__ __forceinline__ void xcd_barrier(const XcdBarrier& b) {
;     asm volatile("s_waitcnt vmcnt(0)" ::: "memory");
;     __syncthreads();
; __global__ void __launch_bounds__(512) mega(Args a) {
;     ...
;   for (int ph = a.ph_lo; ph < a.ph_hi; ++ph) {
;     if (ph > a.ph_lo) xcd_barrier(xb);
.LBB0_24:
	s_setprio 0
	s_waitcnt vmcnt(0)
	s_barrier

; #define LAS __attribute__((address_space(3)))
; __global__ void __launch_bounds__(512) mega(Args a) {
;     ...
;     if ((PHMASK & 2) && sub == 0) {
;       PH_LOCALS
;       pg8::Gemm g{H, WinT + (size_t)l * NIN * DM, MT, NIN, DM, DM, DM};
;       pg8::StaticOrder S; S.init(MT, NIN, G, cu);
;       { const f32x4* bg = (const f32x4*)(b_gate + (size_t)l * 3 * DM); LAS f32x4* bl = (LAS f32x4*)(lds + LDS_BIAS);
;         for (int i = tid; i < 3 * DM / 4; i += 512) bl[i] = bg[i];
;         __syncthreads(); }
.LBB0_329:
	s_andn2_b64 vcc, exec, s[4:5]
	s_cbranch_vccnz .LBB0_25
	v_readfirstlane_b32 s0, v225
	s_nop 3
	s_cmp_lt_u32 s0, 0x100
	s_cbranch_scc1 .Lip_prio_done
	s_setprio 1
.Lip_prio_done:
	v_mov_b32_e32 v0, v225
	s_movk_i32 s0, 0x5ff
	s_mov_b32 s17, s78
	s_mov_b32 s23, s68
	s_mov_b32 s4, s29
	v_cmp_lt_i32_e32 vcc, s0, v0
	v_lshlrev_b32_e32 v4, 4, v0
	s_and_saveexec_b64 s[0:1], vcc
	s_xor_b64 s[0:1], exec, s[0:1]
	v_lshlrev_b32_e32 v4, 4, v0
	s_or_saveexec_b64 s[0:1], s[0:1]
	v_ashrrev_i32_e32 v1, 31, v0
	s_xor_b64 exec, exec, s[0:1]
	s_cbranch_execz .LBB0_336
	v_readlane_b32 s2, v251, 56
	v_readlane_b32 s3, v251, 57
	s_mul_hi_i32 s3, s2, 0x6000
	s_mulk_i32 s2, 0x6000
	s_add_u32 s2, s86, s2
	s_addc_u32 s3, s87, s3
	v_lshl_add_u64 v[2:3], v[0:1], 4, s[2:3]
	v_readlane_b32 s2, v251, 11
	v_add_u32_e32 v5, 0xfffffe00, v0
	s_nop 0
	v_add_u32_e32 v6, s2, v4
	s_mov_b64 s[2:3], 0
